# fox_cumsum kmax: coalesced 8-lane-per-row loads with DPP row sums (was per-thread rows)
# speedup vs baseline: 1.0518x; 1.0311x over previous
; DI void unpack8(uint4 v, float* f) { f[0] = bflo(v.x); f[1] = bfhi(v.x); f[2] = bflo(v.y); f[3] = bfhi(v.y); f[4] = bflo(v.z); f[5] = bfhi(v.z); f[6] = bflo(v.w); f[7] = bfhi(v.w); }
; DI float shx(float v, int m, int lane) { return __int_as_float(__builtin_amdgcn_ds_bpermute((lane ^ m) << 2, __float_as_int(v))); }
; DI void fox_cumsum_unit(const Params& p, int hf, int bl, int fh, unsigned char* shm, int tid) {
;     ...
;   { float* fc = (float*)(wsb + WS_FC) + (size_t)(bl * 8 + fh) * SEQ + tid * 16;
; #pragma unroll
;     for (int e = 0; e < 16; e += 4) { float4 w4; w4.x = v[e] + ex; w4.y = v[e + 1] + ex; w4.z = v[e + 2] + ex; w4.w = v[e + 3] + ex; *(float4*)(fc + e) = w4; } }
;   const bf16_t* kb = (const bf16_t*)(wsb + WS_PROJ) + (size_t)(bl * SEQ + tid * 16) * NP + C_FK + fh * 64;
;   float kmx = 0.f;
; #pragma unroll 4
;   for (int e = 0; e < 16; ++e) {
;     float ssum = 0.f;
; #pragma unroll
;     for (int q = 0; q < 8; ++q) { float f[8]; unpack8(*(const uint4*)(kb + (size_t)e * NP + q * 8), f);
; #pragma unroll
;       for (int z = 0; z < 8; ++z) ssum += f[z] * f[z]; }
;     kmx = fmaxf(kmx, ssum);
;   }
; #pragma unroll
;   for (int o = 32; o >= 1; o >>= 1) kmx = fmaxf(kmx, shx(kmx, o, lane));
.LBB0_319:
	s_or_b64 exec, exec, s[4:5]
	v_cmp_gt_u32_e64 s[0:1], 32, v18
	v_readlane_b32 s6, v253, 34
	v_ashrrev_i32_e32 v1, 31, v0
	v_cndmask_b32_e64 v18, v20, v19, s[0:1]
	s_and_b32 s0, s24, -8
	s_or_b32 s4, s0, s2
	s_ashr_i32 s5, s4, 31
	s_lshl_b64 s[0:1], s[4:5], 15
	v_add_f32_e32 v18, v18, v21
	s_add_u32 s0, s6, s0
	v_readlane_b32 s6, v253, 35
	v_sub_f32_e32 v22, v18, v5
	s_addc_u32 s1, s6, s1
	v_lshl_add_u64 v[24:25], v[0:1], 2, s[0:1]
	v_pk_add_f32 v[18:19], v[2:3], v[22:23] op_sel_hi:[1,0]
	v_pk_add_f32 v[2:3], v[6:7], v[22:23] op_sel_hi:[1,0]
	v_pk_add_f32 v[4:5], v[4:5], v[22:23] op_sel_hi:[1,0]
	global_store_dwordx4 v[24:25], v[2:5], off offset:48
	s_mov_b32 s9, s3
	v_mov_b32_e32 v160, v161
	v_add_u32_e32 v2, s8, v0
	v_mov_b64_e32 v[0:1], s[38:39]
	v_mad_i64_i32 v[34:35], s[0:1], v2, s65, 0
	v_mad_i64_i32 v[0:1], s[0:1], v2, s65, v[0:1]
	s_lshl_b32 s8, s2, 7
	v_lshl_add_u64 v[0:1], v[0:1], 0, s[8:9]
	s_mov_b64 s[0:1], 0x1c00
	s_mov_b32 s59, -8
	v_pk_add_f32 v[20:21], v[16:17], v[22:23] op_sel_hi:[1,0]
	v_pk_add_f32 v[14:15], v[14:15], v[22:23] op_sel_hi:[1,0]
	v_pk_add_f32 v[16:17], v[12:13], v[22:23] op_sel_hi:[1,0]
	v_pk_add_f32 v[10:11], v[10:11], v[22:23] op_sel_hi:[1,0]
	v_pk_add_f32 v[12:13], v[8:9], v[22:23] op_sel_hi:[1,0]
	v_lshl_add_u64 v[32:33], v[0:1], 0, s[0:1]
	s_mov_b32 s9, 1
	s_mov_b32 s60, 0
	s_mov_b64 s[10:11], 0
	v_mov_b64_e32 v[0:1], v[160:161]
	global_store_dwordx4 v[24:25], v[18:21], off
	global_store_dwordx4 v[24:25], v[14:17], off offset:16
	global_store_dwordx4 v[24:25], v[10:13], off offset:32
	s_waitcnt vmcnt(0)
	v_lshrrev_b32_e32 v0, 3, v46
	v_and_b32_e32 v1, 7, v46
	v_mul_u32_u24_e32 v0, 0x3400, v0
	v_lshl_add_u32 v49, v1, 4, v0
	s_lshl_b32 s0, s24, 10
	s_and_b32 s0, s0, 0xffffe000
	s_mul_hi_u32 s1, s0, 0x3400
	s_mul_i32 s0, s0, 0x3400
	s_lshl_b32 s6, s2, 7
	s_add_u32 s0, s0, s6
	s_addc_u32 s1, s1, 0
	s_add_u32 s0, s0, 0x1c00
	s_addc_u32 s1, s1, 0
	s_add_u32 s10, s38, s0
	s_addc_u32 s11, s39, s1
	v_mov_b32_e32 v14, 0
	global_load_dwordx4 v[50:53], v49, s[10:11]
	s_add_u32 s10, s10, 0xd0000
	s_addc_u32 s11, s11, 0
	global_load_dwordx4 v[54:57], v49, s[10:11]
	s_add_u32 s10, s10, 0xd0000
	s_addc_u32 s11, s11, 0
	global_load_dwordx4 v[58:61], v49, s[10:11]
	s_add_u32 s10, s10, 0xd0000
	s_addc_u32 s11, s11, 0
	global_load_dwordx4 v[62:65], v49, s[10:11]
	s_add_u32 s10, s10, 0xd0000
	s_addc_u32 s11, s11, 0
	global_load_dwordx4 v[66:69], v49, s[10:11]
	s_add_u32 s10, s10, 0xd0000
	s_addc_u32 s11, s11, 0
	global_load_dwordx4 v[70:73], v49, s[10:11]
	s_add_u32 s10, s10, 0xd0000
	s_addc_u32 s11, s11, 0
	global_load_dwordx4 v[74:77], v49, s[10:11]
	s_add_u32 s10, s10, 0xd0000
	s_addc_u32 s11, s11, 0
	global_load_dwordx4 v[78:81], v49, s[10:11]
	s_add_u32 s10, s10, 0xd0000
	s_addc_u32 s11, s11, 0
	global_load_dwordx4 v[82:85], v49, s[10:11]
	s_add_u32 s10, s10, 0xd0000
	s_addc_u32 s11, s11, 0
	global_load_dwordx4 v[86:89], v49, s[10:11]
	s_add_u32 s10, s10, 0xd0000
	s_addc_u32 s11, s11, 0
	global_load_dwordx4 v[90:93], v49, s[10:11]
	s_add_u32 s10, s10, 0xd0000
	s_addc_u32 s11, s11, 0
	global_load_dwordx4 v[94:97], v49, s[10:11]
	s_add_u32 s10, s10, 0xd0000
	s_addc_u32 s11, s11, 0
	global_load_dwordx4 v[98:101], v49, s[10:11]
	s_add_u32 s10, s10, 0xd0000
	s_addc_u32 s11, s11, 0
	global_load_dwordx4 v[102:105], v49, s[10:11]
	s_add_u32 s10, s10, 0xd0000
	s_addc_u32 s11, s11, 0
	global_load_dwordx4 v[106:109], v49, s[10:11]
	s_add_u32 s10, s10, 0xd0000
	s_addc_u32 s11, s11, 0
	global_load_dwordx4 v[110:113], v49, s[10:11]
	s_add_u32 s10, s10, 0xd0000
	s_addc_u32 s11, s11, 0
	s_mov_b32 s9, 7
.Lkmx_loop:
	s_waitcnt vmcnt(14)
	v_lshlrev_b32_e32 v2, 16, v50
	v_lshlrev_b32_e32 v6, 16, v54
	v_lshlrev_b32_e32 v3, 16, v51
	v_lshlrev_b32_e32 v7, 16, v55
	v_lshlrev_b32_e32 v4, 16, v52
	v_lshlrev_b32_e32 v8, 16, v56
	v_lshlrev_b32_e32 v5, 16, v53
	v_lshlrev_b32_e32 v9, 16, v57
	v_and_b32_e32 v50, 0xffff0000, v50
	v_and_b32_e32 v54, 0xffff0000, v54
	v_and_b32_e32 v51, 0xffff0000, v51
	v_and_b32_e32 v55, 0xffff0000, v55
	v_and_b32_e32 v52, 0xffff0000, v52
	v_and_b32_e32 v56, 0xffff0000, v56
	v_and_b32_e32 v53, 0xffff0000, v53
	v_and_b32_e32 v57, 0xffff0000, v57
	v_mul_f32_e32 v10, v2, v2
	v_mul_f32_e32 v11, v6, v6
	v_fmac_f32_e32 v10, v50, v50
	v_fmac_f32_e32 v11, v54, v54
	v_fmac_f32_e32 v10, v3, v3
	v_fmac_f32_e32 v11, v7, v7
	v_fmac_f32_e32 v10, v51, v51
	v_fmac_f32_e32 v11, v55, v55
	v_fmac_f32_e32 v10, v4, v4
	v_fmac_f32_e32 v11, v8, v8
	v_fmac_f32_e32 v10, v52, v52
	v_fmac_f32_e32 v11, v56, v56
	v_fmac_f32_e32 v10, v5, v5
	v_fmac_f32_e32 v11, v9, v9
	v_fmac_f32_e32 v10, v53, v53
	v_fmac_f32_e32 v11, v57, v57
	global_load_dwordx4 v[50:53], v49, s[10:11]
	s_add_u32 s10, s10, 0xd0000
	s_addc_u32 s11, s11, 0
	global_load_dwordx4 v[54:57], v49, s[10:11]
	s_add_u32 s10, s10, 0xd0000
	s_addc_u32 s11, s11, 0
	v_add_f32_dpp v10, v10, v10 quad_perm:[1,0,3,2] row_mask:0xf bank_mask:0xf
	v_add_f32_dpp v11, v11, v11 quad_perm:[1,0,3,2] row_mask:0xf bank_mask:0xf
	s_nop 0
	v_add_f32_dpp v10, v10, v10 quad_perm:[2,3,0,1] row_mask:0xf bank_mask:0xf
	v_add_f32_dpp v11, v11, v11 quad_perm:[2,3,0,1] row_mask:0xf bank_mask:0xf
	s_nop 0
	v_add_f32_dpp v10, v10, v10 row_half_mirror row_mask:0xf bank_mask:0xf
	v_add_f32_dpp v11, v11, v11 row_half_mirror row_mask:0xf bank_mask:0xf
	s_nop 0
	v_max3_f32 v14, v14, v10, v11
	s_waitcnt vmcnt(14)
; DI void unpack8(uint4 v, float* f) { f[0] = bflo(v.x); f[1] = bfhi(v.x); f[2] = bflo(v.y); f[3] = bfhi(v.y); f[4] = bflo(v.z); f[5] = bfhi(v.z); f[6] = bflo(v.w); f[7] = bfhi(v.w); }
; DI float shx(float v, int m, int lane) { return __int_as_float(__builtin_amdgcn_ds_bpermute((lane ^ m) << 2, __float_as_int(v))); }
; DI void fox_cumsum_unit(const Params& p, int hf, int bl, int fh, unsigned char* shm, int tid) {
;     ...
;   const bf16_t* kb = (const bf16_t*)(wsb + WS_PROJ) + (size_t)(bl * SEQ + tid * 16) * NP + C_FK + fh * 64;
;   float kmx = 0.f;
; #pragma unroll 4
;   for (int e = 0; e < 16; ++e) {
;     float ssum = 0.f;
; #pragma unroll
;     for (int q = 0; q < 8; ++q) { float f[8]; unpack8(*(const uint4*)(kb + (size_t)e * NP + q * 8), f);
; #pragma unroll
;       for (int z = 0; z < 8; ++z) ssum += f[z] * f[z]; }
;     kmx = fmaxf(kmx, ssum);
;   }
; #pragma unroll
;   for (int o = 32; o >= 1; o >>= 1) kmx = fmaxf(kmx, shx(kmx, o, lane));
	v_lshlrev_b32_e32 v2, 16, v58
	v_lshlrev_b32_e32 v6, 16, v62
	v_lshlrev_b32_e32 v3, 16, v59
	v_lshlrev_b32_e32 v7, 16, v63
	v_lshlrev_b32_e32 v4, 16, v60
	v_lshlrev_b32_e32 v8, 16, v64
	v_lshlrev_b32_e32 v5, 16, v61
	v_lshlrev_b32_e32 v9, 16, v65
	v_and_b32_e32 v58, 0xffff0000, v58
	v_and_b32_e32 v62, 0xffff0000, v62
	v_and_b32_e32 v59, 0xffff0000, v59
	v_and_b32_e32 v63, 0xffff0000, v63
	v_and_b32_e32 v60, 0xffff0000, v60
	v_and_b32_e32 v64, 0xffff0000, v64
	v_and_b32_e32 v61, 0xffff0000, v61
	v_and_b32_e32 v65, 0xffff0000, v65
	v_mul_f32_e32 v10, v2, v2
	v_mul_f32_e32 v11, v6, v6
	v_fmac_f32_e32 v10, v58, v58
	v_fmac_f32_e32 v11, v62, v62
	v_fmac_f32_e32 v10, v3, v3
	v_fmac_f32_e32 v11, v7, v7
	v_fmac_f32_e32 v10, v59, v59
	v_fmac_f32_e32 v11, v63, v63
	v_fmac_f32_e32 v10, v4, v4
	v_fmac_f32_e32 v11, v8, v8
	v_fmac_f32_e32 v10, v60, v60
	v_fmac_f32_e32 v11, v64, v64
	v_fmac_f32_e32 v10, v5, v5
	v_fmac_f32_e32 v11, v9, v9
	v_fmac_f32_e32 v10, v61, v61
	v_fmac_f32_e32 v11, v65, v65
	global_load_dwordx4 v[58:61], v49, s[10:11]
	s_add_u32 s10, s10, 0xd0000
	s_addc_u32 s11, s11, 0
	global_load_dwordx4 v[62:65], v49, s[10:11]
	s_add_u32 s10, s10, 0xd0000
	s_addc_u32 s11, s11, 0
	v_add_f32_dpp v10, v10, v10 quad_perm:[1,0,3,2] row_mask:0xf bank_mask:0xf
	v_add_f32_dpp v11, v11, v11 quad_perm:[1,0,3,2] row_mask:0xf bank_mask:0xf
	s_nop 0
	v_add_f32_dpp v10, v10, v10 quad_perm:[2,3,0,1] row_mask:0xf bank_mask:0xf
	v_add_f32_dpp v11, v11, v11 quad_perm:[2,3,0,1] row_mask:0xf bank_mask:0xf
	s_nop 0
	v_add_f32_dpp v10, v10, v10 row_half_mirror row_mask:0xf bank_mask:0xf
	v_add_f32_dpp v11, v11, v11 row_half_mirror row_mask:0xf bank_mask:0xf
	s_nop 0
	v_max3_f32 v14, v14, v10, v11
	s_waitcnt vmcnt(14)
	v_lshlrev_b32_e32 v2, 16, v66
	v_lshlrev_b32_e32 v6, 16, v70
	v_lshlrev_b32_e32 v3, 16, v67
	v_lshlrev_b32_e32 v7, 16, v71
	v_lshlrev_b32_e32 v4, 16, v68
	v_lshlrev_b32_e32 v8, 16, v72
	v_lshlrev_b32_e32 v5, 16, v69
	v_lshlrev_b32_e32 v9, 16, v73
	v_and_b32_e32 v66, 0xffff0000, v66
	v_and_b32_e32 v70, 0xffff0000, v70
	v_and_b32_e32 v67, 0xffff0000, v67
	v_and_b32_e32 v71, 0xffff0000, v71
	v_and_b32_e32 v68, 0xffff0000, v68
	v_and_b32_e32 v72, 0xffff0000, v72
	v_and_b32_e32 v69, 0xffff0000, v69
	v_and_b32_e32 v73, 0xffff0000, v73
	v_mul_f32_e32 v10, v2, v2
	v_mul_f32_e32 v11, v6, v6
	v_fmac_f32_e32 v10, v66, v66
	v_fmac_f32_e32 v11, v70, v70
	v_fmac_f32_e32 v10, v3, v3
	v_fmac_f32_e32 v11, v7, v7
	v_fmac_f32_e32 v10, v67, v67
	v_fmac_f32_e32 v11, v71, v71
	v_fmac_f32_e32 v10, v4, v4
	v_fmac_f32_e32 v11, v8, v8
	v_fmac_f32_e32 v10, v68, v68
	v_fmac_f32_e32 v11, v72, v72
	v_fmac_f32_e32 v10, v5, v5
	v_fmac_f32_e32 v11, v9, v9
	v_fmac_f32_e32 v10, v69, v69
	v_fmac_f32_e32 v11, v73, v73
	global_load_dwordx4 v[66:69], v49, s[10:11]
	s_add_u32 s10, s10, 0xd0000
	s_addc_u32 s11, s11, 0
	global_load_dwordx4 v[70:73], v49, s[10:11]
	s_add_u32 s10, s10, 0xd0000
	s_addc_u32 s11, s11, 0
	v_add_f32_dpp v10, v10, v10 quad_perm:[1,0,3,2] row_mask:0xf bank_mask:0xf
	v_add_f32_dpp v11, v11, v11 quad_perm:[1,0,3,2] row_mask:0xf bank_mask:0xf
	s_nop 0
	v_add_f32_dpp v10, v10, v10 quad_perm:[2,3,0,1] row_mask:0xf bank_mask:0xf
	v_add_f32_dpp v11, v11, v11 quad_perm:[2,3,0,1] row_mask:0xf bank_mask:0xf
	s_nop 0
	v_add_f32_dpp v10, v10, v10 row_half_mirror row_mask:0xf bank_mask:0xf
	v_add_f32_dpp v11, v11, v11 row_half_mirror row_mask:0xf bank_mask:0xf
	s_nop 0
	v_max3_f32 v14, v14, v10, v11
	s_waitcnt vmcnt(14)
	v_lshlrev_b32_e32 v2, 16, v74
	v_lshlrev_b32_e32 v6, 16, v78
	v_lshlrev_b32_e32 v3, 16, v75
	v_lshlrev_b32_e32 v7, 16, v79
	v_lshlrev_b32_e32 v4, 16, v76
	v_lshlrev_b32_e32 v8, 16, v80
	v_lshlrev_b32_e32 v5, 16, v77
	v_lshlrev_b32_e32 v9, 16, v81
	v_and_b32_e32 v74, 0xffff0000, v74
	v_and_b32_e32 v78, 0xffff0000, v78
	v_and_b32_e32 v75, 0xffff0000, v75
	v_and_b32_e32 v79, 0xffff0000, v79
	v_and_b32_e32 v76, 0xffff0000, v76
	v_and_b32_e32 v80, 0xffff0000, v80
	v_and_b32_e32 v77, 0xffff0000, v77
	v_and_b32_e32 v81, 0xffff0000, v81
	v_mul_f32_e32 v10, v2, v2
	v_mul_f32_e32 v11, v6, v6
	v_fmac_f32_e32 v10, v74, v74
	v_fmac_f32_e32 v11, v78, v78
	v_fmac_f32_e32 v10, v3, v3
	v_fmac_f32_e32 v11, v7, v7
	v_fmac_f32_e32 v10, v75, v75
	v_fmac_f32_e32 v11, v79, v79
	v_fmac_f32_e32 v10, v4, v4
	v_fmac_f32_e32 v11, v8, v8
	v_fmac_f32_e32 v10, v76, v76
	v_fmac_f32_e32 v11, v80, v80
	v_fmac_f32_e32 v10, v5, v5
	v_fmac_f32_e32 v11, v9, v9
	v_fmac_f32_e32 v10, v77, v77
	v_fmac_f32_e32 v11, v81, v81
	global_load_dwordx4 v[74:77], v49, s[10:11]
	s_add_u32 s10, s10, 0xd0000
	s_addc_u32 s11, s11, 0
	global_load_dwordx4 v[78:81], v49, s[10:11]
	s_add_u32 s10, s10, 0xd0000
	s_addc_u32 s11, s11, 0
	v_add_f32_dpp v10, v10, v10 quad_perm:[1,0,3,2] row_mask:0xf bank_mask:0xf
	v_add_f32_dpp v11, v11, v11 quad_perm:[1,0,3,2] row_mask:0xf bank_mask:0xf
	s_nop 0
	v_add_f32_dpp v10, v10, v10 quad_perm:[2,3,0,1] row_mask:0xf bank_mask:0xf
	v_add_f32_dpp v11, v11, v11 quad_perm:[2,3,0,1] row_mask:0xf bank_mask:0xf
	s_nop 0
	v_add_f32_dpp v10, v10, v10 row_half_mirror row_mask:0xf bank_mask:0xf
	v_add_f32_dpp v11, v11, v11 row_half_mirror row_mask:0xf bank_mask:0xf
	s_nop 0
	v_max3_f32 v14, v14, v10, v11
	s_waitcnt vmcnt(14)
; DI void unpack8(uint4 v, float* f) { f[0] = bflo(v.x); f[1] = bfhi(v.x); f[2] = bflo(v.y); f[3] = bfhi(v.y); f[4] = bflo(v.z); f[5] = bfhi(v.z); f[6] = bflo(v.w); f[7] = bfhi(v.w); }
; DI float shx(float v, int m, int lane) { return __int_as_float(__builtin_amdgcn_ds_bpermute((lane ^ m) << 2, __float_as_int(v))); }
; DI void fox_cumsum_unit(const Params& p, int hf, int bl, int fh, unsigned char* shm, int tid) {
;     ...
;   const bf16_t* kb = (const bf16_t*)(wsb + WS_PROJ) + (size_t)(bl * SEQ + tid * 16) * NP + C_FK + fh * 64;
;   float kmx = 0.f;
; #pragma unroll 4
;   for (int e = 0; e < 16; ++e) {
;     float ssum = 0.f;
; #pragma unroll
;     for (int q = 0; q < 8; ++q) { float f[8]; unpack8(*(const uint4*)(kb + (size_t)e * NP + q * 8), f);
; #pragma unroll
;       for (int z = 0; z < 8; ++z) ssum += f[z] * f[z]; }
;     kmx = fmaxf(kmx, ssum);
;   }
; #pragma unroll
;   for (int o = 32; o >= 1; o >>= 1) kmx = fmaxf(kmx, shx(kmx, o, lane));
	v_lshlrev_b32_e32 v2, 16, v82
	v_lshlrev_b32_e32 v6, 16, v86
	v_lshlrev_b32_e32 v3, 16, v83
	v_lshlrev_b32_e32 v7, 16, v87
	v_lshlrev_b32_e32 v4, 16, v84
	v_lshlrev_b32_e32 v8, 16, v88
	v_lshlrev_b32_e32 v5, 16, v85
	v_lshlrev_b32_e32 v9, 16, v89
	v_and_b32_e32 v82, 0xffff0000, v82
	v_and_b32_e32 v86, 0xffff0000, v86
	v_and_b32_e32 v83, 0xffff0000, v83
	v_and_b32_e32 v87, 0xffff0000, v87
	v_and_b32_e32 v84, 0xffff0000, v84
	v_and_b32_e32 v88, 0xffff0000, v88
	v_and_b32_e32 v85, 0xffff0000, v85
	v_and_b32_e32 v89, 0xffff0000, v89
	v_mul_f32_e32 v10, v2, v2
	v_mul_f32_e32 v11, v6, v6
	v_fmac_f32_e32 v10, v82, v82
	v_fmac_f32_e32 v11, v86, v86
	v_fmac_f32_e32 v10, v3, v3
	v_fmac_f32_e32 v11, v7, v7
	v_fmac_f32_e32 v10, v83, v83
	v_fmac_f32_e32 v11, v87, v87
	v_fmac_f32_e32 v10, v4, v4
	v_fmac_f32_e32 v11, v8, v8
	v_fmac_f32_e32 v10, v84, v84
	v_fmac_f32_e32 v11, v88, v88
	v_fmac_f32_e32 v10, v5, v5
	v_fmac_f32_e32 v11, v9, v9
	v_fmac_f32_e32 v10, v85, v85
	v_fmac_f32_e32 v11, v89, v89
	global_load_dwordx4 v[82:85], v49, s[10:11]
	s_add_u32 s10, s10, 0xd0000
	s_addc_u32 s11, s11, 0
	global_load_dwordx4 v[86:89], v49, s[10:11]
	s_add_u32 s10, s10, 0xd0000
	s_addc_u32 s11, s11, 0
	v_add_f32_dpp v10, v10, v10 quad_perm:[1,0,3,2] row_mask:0xf bank_mask:0xf
	v_add_f32_dpp v11, v11, v11 quad_perm:[1,0,3,2] row_mask:0xf bank_mask:0xf
	s_nop 0
	v_add_f32_dpp v10, v10, v10 quad_perm:[2,3,0,1] row_mask:0xf bank_mask:0xf
	v_add_f32_dpp v11, v11, v11 quad_perm:[2,3,0,1] row_mask:0xf bank_mask:0xf
	s_nop 0
	v_add_f32_dpp v10, v10, v10 row_half_mirror row_mask:0xf bank_mask:0xf
	v_add_f32_dpp v11, v11, v11 row_half_mirror row_mask:0xf bank_mask:0xf
	s_nop 0
	v_max3_f32 v14, v14, v10, v11
	s_waitcnt vmcnt(14)
	v_lshlrev_b32_e32 v2, 16, v90
	v_lshlrev_b32_e32 v6, 16, v94
	v_lshlrev_b32_e32 v3, 16, v91
	v_lshlrev_b32_e32 v7, 16, v95
	v_lshlrev_b32_e32 v4, 16, v92
	v_lshlrev_b32_e32 v8, 16, v96
	v_lshlrev_b32_e32 v5, 16, v93
	v_lshlrev_b32_e32 v9, 16, v97
	v_and_b32_e32 v90, 0xffff0000, v90
	v_and_b32_e32 v94, 0xffff0000, v94
	v_and_b32_e32 v91, 0xffff0000, v91
	v_and_b32_e32 v95, 0xffff0000, v95
	v_and_b32_e32 v92, 0xffff0000, v92
	v_and_b32_e32 v96, 0xffff0000, v96
	v_and_b32_e32 v93, 0xffff0000, v93
	v_and_b32_e32 v97, 0xffff0000, v97
	v_mul_f32_e32 v10, v2, v2
	v_mul_f32_e32 v11, v6, v6
	v_fmac_f32_e32 v10, v90, v90
	v_fmac_f32_e32 v11, v94, v94
	v_fmac_f32_e32 v10, v3, v3
	v_fmac_f32_e32 v11, v7, v7
	v_fmac_f32_e32 v10, v91, v91
	v_fmac_f32_e32 v11, v95, v95
	v_fmac_f32_e32 v10, v4, v4
	v_fmac_f32_e32 v11, v8, v8
	v_fmac_f32_e32 v10, v92, v92
	v_fmac_f32_e32 v11, v96, v96
	v_fmac_f32_e32 v10, v5, v5
	v_fmac_f32_e32 v11, v9, v9
	v_fmac_f32_e32 v10, v93, v93
	v_fmac_f32_e32 v11, v97, v97
	global_load_dwordx4 v[90:93], v49, s[10:11]
	s_add_u32 s10, s10, 0xd0000
	s_addc_u32 s11, s11, 0
	global_load_dwordx4 v[94:97], v49, s[10:11]
	s_add_u32 s10, s10, 0xd0000
	s_addc_u32 s11, s11, 0
	v_add_f32_dpp v10, v10, v10 quad_perm:[1,0,3,2] row_mask:0xf bank_mask:0xf
	v_add_f32_dpp v11, v11, v11 quad_perm:[1,0,3,2] row_mask:0xf bank_mask:0xf
	s_nop 0
	v_add_f32_dpp v10, v10, v10 quad_perm:[2,3,0,1] row_mask:0xf bank_mask:0xf
	v_add_f32_dpp v11, v11, v11 quad_perm:[2,3,0,1] row_mask:0xf bank_mask:0xf
	s_nop 0
	v_add_f32_dpp v10, v10, v10 row_half_mirror row_mask:0xf bank_mask:0xf
	v_add_f32_dpp v11, v11, v11 row_half_mirror row_mask:0xf bank_mask:0xf
	s_nop 0
	v_max3_f32 v14, v14, v10, v11
	s_waitcnt vmcnt(14)
	v_lshlrev_b32_e32 v2, 16, v98
	v_lshlrev_b32_e32 v6, 16, v102
	v_lshlrev_b32_e32 v3, 16, v99
	v_lshlrev_b32_e32 v7, 16, v103
	v_lshlrev_b32_e32 v4, 16, v100
	v_lshlrev_b32_e32 v8, 16, v104
	v_lshlrev_b32_e32 v5, 16, v101
	v_lshlrev_b32_e32 v9, 16, v105
	v_and_b32_e32 v98, 0xffff0000, v98
	v_and_b32_e32 v102, 0xffff0000, v102
	v_and_b32_e32 v99, 0xffff0000, v99
	v_and_b32_e32 v103, 0xffff0000, v103
	v_and_b32_e32 v100, 0xffff0000, v100
	v_and_b32_e32 v104, 0xffff0000, v104
	v_and_b32_e32 v101, 0xffff0000, v101
	v_and_b32_e32 v105, 0xffff0000, v105
	v_mul_f32_e32 v10, v2, v2
	v_mul_f32_e32 v11, v6, v6
	v_fmac_f32_e32 v10, v98, v98
	v_fmac_f32_e32 v11, v102, v102
	v_fmac_f32_e32 v10, v3, v3
	v_fmac_f32_e32 v11, v7, v7
	v_fmac_f32_e32 v10, v99, v99
	v_fmac_f32_e32 v11, v103, v103
	v_fmac_f32_e32 v10, v4, v4
	v_fmac_f32_e32 v11, v8, v8
	v_fmac_f32_e32 v10, v100, v100
	v_fmac_f32_e32 v11, v104, v104
	v_fmac_f32_e32 v10, v5, v5
	v_fmac_f32_e32 v11, v9, v9
	v_fmac_f32_e32 v10, v101, v101
	v_fmac_f32_e32 v11, v105, v105
	global_load_dwordx4 v[98:101], v49, s[10:11]
	s_add_u32 s10, s10, 0xd0000
	s_addc_u32 s11, s11, 0
	global_load_dwordx4 v[102:105], v49, s[10:11]
	s_add_u32 s10, s10, 0xd0000
	s_addc_u32 s11, s11, 0
	v_add_f32_dpp v10, v10, v10 quad_perm:[1,0,3,2] row_mask:0xf bank_mask:0xf
	v_add_f32_dpp v11, v11, v11 quad_perm:[1,0,3,2] row_mask:0xf bank_mask:0xf
	s_nop 0
	v_add_f32_dpp v10, v10, v10 quad_perm:[2,3,0,1] row_mask:0xf bank_mask:0xf
	v_add_f32_dpp v11, v11, v11 quad_perm:[2,3,0,1] row_mask:0xf bank_mask:0xf
	s_nop 0
	v_add_f32_dpp v10, v10, v10 row_half_mirror row_mask:0xf bank_mask:0xf
	v_add_f32_dpp v11, v11, v11 row_half_mirror row_mask:0xf bank_mask:0xf
	s_nop 0
	v_max3_f32 v14, v14, v10, v11
	s_waitcnt vmcnt(14)
	v_lshlrev_b32_e32 v2, 16, v106
	v_lshlrev_b32_e32 v6, 16, v110
	v_lshlrev_b32_e32 v3, 16, v107
	v_lshlrev_b32_e32 v7, 16, v111
	v_lshlrev_b32_e32 v4, 16, v108
	v_lshlrev_b32_e32 v8, 16, v112
	v_lshlrev_b32_e32 v5, 16, v109
	v_lshlrev_b32_e32 v9, 16, v113
	v_and_b32_e32 v106, 0xffff0000, v106
	v_and_b32_e32 v110, 0xffff0000, v110
	v_and_b32_e32 v107, 0xffff0000, v107
	v_and_b32_e32 v111, 0xffff0000, v111
	v_and_b32_e32 v108, 0xffff0000, v108
	v_and_b32_e32 v112, 0xffff0000, v112
	v_and_b32_e32 v109, 0xffff0000, v109
	v_and_b32_e32 v113, 0xffff0000, v113
	v_mul_f32_e32 v10, v2, v2
	v_mul_f32_e32 v11, v6, v6
	v_fmac_f32_e32 v10, v106, v106
	v_fmac_f32_e32 v11, v110, v110
	v_fmac_f32_e32 v10, v3, v3
	v_fmac_f32_e32 v11, v7, v7
	v_fmac_f32_e32 v10, v107, v107
	v_fmac_f32_e32 v11, v111, v111
	v_fmac_f32_e32 v10, v4, v4
	v_fmac_f32_e32 v11, v8, v8
	v_fmac_f32_e32 v10, v108, v108
	v_fmac_f32_e32 v11, v112, v112
	v_fmac_f32_e32 v10, v5, v5
	v_fmac_f32_e32 v11, v9, v9
	v_fmac_f32_e32 v10, v109, v109
	v_fmac_f32_e32 v11, v113, v113
	global_load_dwordx4 v[106:109], v49, s[10:11]
	s_add_u32 s10, s10, 0xd0000
	s_addc_u32 s11, s11, 0
	global_load_dwordx4 v[110:113], v49, s[10:11]
	s_add_u32 s10, s10, 0xd0000
	s_addc_u32 s11, s11, 0
	v_add_f32_dpp v10, v10, v10 quad_perm:[1,0,3,2] row_mask:0xf bank_mask:0xf
	v_add_f32_dpp v11, v11, v11 quad_perm:[1,0,3,2] row_mask:0xf bank_mask:0xf
	s_nop 0
	v_add_f32_dpp v10, v10, v10 quad_perm:[2,3,0,1] row_mask:0xf bank_mask:0xf
	v_add_f32_dpp v11, v11, v11 quad_perm:[2,3,0,1] row_mask:0xf bank_mask:0xf
	s_nop 0
	v_add_f32_dpp v10, v10, v10 row_half_mirror row_mask:0xf bank_mask:0xf
	v_add_f32_dpp v11, v11, v11 row_half_mirror row_mask:0xf bank_mask:0xf
	s_nop 0
	v_max3_f32 v14, v14, v10, v11
	s_add_i32 s9, s9, -1
	s_cmp_lg_u32 s9, 0
	s_cbranch_scc1 .Lkmx_loop
; DI void unpack8(uint4 v, float* f) { f[0] = bflo(v.x); f[1] = bfhi(v.x); f[2] = bflo(v.y); f[3] = bfhi(v.y); f[4] = bflo(v.z); f[5] = bfhi(v.z); f[6] = bflo(v.w); f[7] = bfhi(v.w); }
; DI float shx(float v, int m, int lane) { return __int_as_float(__builtin_amdgcn_ds_bpermute((lane ^ m) << 2, __float_as_int(v))); }
; DI void fox_cumsum_unit(const Params& p, int hf, int bl, int fh, unsigned char* shm, int tid) {
;     ...
;   const bf16_t* kb = (const bf16_t*)(wsb + WS_PROJ) + (size_t)(bl * SEQ + tid * 16) * NP + C_FK + fh * 64;
;   float kmx = 0.f;
; #pragma unroll 4
;   for (int e = 0; e < 16; ++e) {
;     float ssum = 0.f;
; #pragma unroll
;     for (int q = 0; q < 8; ++q) { float f[8]; unpack8(*(const uint4*)(kb + (size_t)e * NP + q * 8), f);
; #pragma unroll
;       for (int z = 0; z < 8; ++z) ssum += f[z] * f[z]; }
;     kmx = fmaxf(kmx, ssum);
;   }
; #pragma unroll
;   for (int o = 32; o >= 1; o >>= 1) kmx = fmaxf(kmx, shx(kmx, o, lane));
	s_waitcnt vmcnt(14)
	v_lshlrev_b32_e32 v2, 16, v50
	v_lshlrev_b32_e32 v6, 16, v54
	v_lshlrev_b32_e32 v3, 16, v51
	v_lshlrev_b32_e32 v7, 16, v55
	v_lshlrev_b32_e32 v4, 16, v52
	v_lshlrev_b32_e32 v8, 16, v56
	v_lshlrev_b32_e32 v5, 16, v53
	v_lshlrev_b32_e32 v9, 16, v57
	v_and_b32_e32 v50, 0xffff0000, v50
	v_and_b32_e32 v54, 0xffff0000, v54
	v_and_b32_e32 v51, 0xffff0000, v51
	v_and_b32_e32 v55, 0xffff0000, v55
	v_and_b32_e32 v52, 0xffff0000, v52
	v_and_b32_e32 v56, 0xffff0000, v56
	v_and_b32_e32 v53, 0xffff0000, v53
	v_and_b32_e32 v57, 0xffff0000, v57
	v_mul_f32_e32 v10, v2, v2
	v_mul_f32_e32 v11, v6, v6
	v_fmac_f32_e32 v10, v50, v50
	v_fmac_f32_e32 v11, v54, v54
	v_fmac_f32_e32 v10, v3, v3
	v_fmac_f32_e32 v11, v7, v7
	v_fmac_f32_e32 v10, v51, v51
	v_fmac_f32_e32 v11, v55, v55
	v_fmac_f32_e32 v10, v4, v4
	v_fmac_f32_e32 v11, v8, v8
	v_fmac_f32_e32 v10, v52, v52
	v_fmac_f32_e32 v11, v56, v56
	v_fmac_f32_e32 v10, v5, v5
	v_fmac_f32_e32 v11, v9, v9
	v_fmac_f32_e32 v10, v53, v53
	v_fmac_f32_e32 v11, v57, v57
	s_nop 1
	v_add_f32_dpp v10, v10, v10 quad_perm:[1,0,3,2] row_mask:0xf bank_mask:0xf
	v_add_f32_dpp v11, v11, v11 quad_perm:[1,0,3,2] row_mask:0xf bank_mask:0xf
	s_nop 0
	v_add_f32_dpp v10, v10, v10 quad_perm:[2,3,0,1] row_mask:0xf bank_mask:0xf
	v_add_f32_dpp v11, v11, v11 quad_perm:[2,3,0,1] row_mask:0xf bank_mask:0xf
	s_nop 0
	v_add_f32_dpp v10, v10, v10 row_half_mirror row_mask:0xf bank_mask:0xf
	v_add_f32_dpp v11, v11, v11 row_half_mirror row_mask:0xf bank_mask:0xf
	s_nop 0
	v_max3_f32 v14, v14, v10, v11
	s_waitcnt vmcnt(12)
	v_lshlrev_b32_e32 v2, 16, v58
	v_lshlrev_b32_e32 v6, 16, v62
	v_lshlrev_b32_e32 v3, 16, v59
	v_lshlrev_b32_e32 v7, 16, v63
	v_lshlrev_b32_e32 v4, 16, v60
	v_lshlrev_b32_e32 v8, 16, v64
	v_lshlrev_b32_e32 v5, 16, v61
	v_lshlrev_b32_e32 v9, 16, v65
	v_and_b32_e32 v58, 0xffff0000, v58
	v_and_b32_e32 v62, 0xffff0000, v62
	v_and_b32_e32 v59, 0xffff0000, v59
	v_and_b32_e32 v63, 0xffff0000, v63
	v_and_b32_e32 v60, 0xffff0000, v60
	v_and_b32_e32 v64, 0xffff0000, v64
	v_and_b32_e32 v61, 0xffff0000, v61
	v_and_b32_e32 v65, 0xffff0000, v65
	v_mul_f32_e32 v10, v2, v2
	v_mul_f32_e32 v11, v6, v6
	v_fmac_f32_e32 v10, v58, v58
	v_fmac_f32_e32 v11, v62, v62
	v_fmac_f32_e32 v10, v3, v3
	v_fmac_f32_e32 v11, v7, v7
	v_fmac_f32_e32 v10, v59, v59
	v_fmac_f32_e32 v11, v63, v63
	v_fmac_f32_e32 v10, v4, v4
	v_fmac_f32_e32 v11, v8, v8
	v_fmac_f32_e32 v10, v60, v60
	v_fmac_f32_e32 v11, v64, v64
	v_fmac_f32_e32 v10, v5, v5
	v_fmac_f32_e32 v11, v9, v9
	v_fmac_f32_e32 v10, v61, v61
	v_fmac_f32_e32 v11, v65, v65
	s_nop 1
	v_add_f32_dpp v10, v10, v10 quad_perm:[1,0,3,2] row_mask:0xf bank_mask:0xf
	v_add_f32_dpp v11, v11, v11 quad_perm:[1,0,3,2] row_mask:0xf bank_mask:0xf
	s_nop 0
	v_add_f32_dpp v10, v10, v10 quad_perm:[2,3,0,1] row_mask:0xf bank_mask:0xf
	v_add_f32_dpp v11, v11, v11 quad_perm:[2,3,0,1] row_mask:0xf bank_mask:0xf
	s_nop 0
	v_add_f32_dpp v10, v10, v10 row_half_mirror row_mask:0xf bank_mask:0xf
	v_add_f32_dpp v11, v11, v11 row_half_mirror row_mask:0xf bank_mask:0xf
	s_nop 0
	v_max3_f32 v14, v14, v10, v11
	s_waitcnt vmcnt(10)
	v_lshlrev_b32_e32 v2, 16, v66
	v_lshlrev_b32_e32 v6, 16, v70
	v_lshlrev_b32_e32 v3, 16, v67
	v_lshlrev_b32_e32 v7, 16, v71
	v_lshlrev_b32_e32 v4, 16, v68
	v_lshlrev_b32_e32 v8, 16, v72
	v_lshlrev_b32_e32 v5, 16, v69
	v_lshlrev_b32_e32 v9, 16, v73
	v_and_b32_e32 v66, 0xffff0000, v66
	v_and_b32_e32 v70, 0xffff0000, v70
	v_and_b32_e32 v67, 0xffff0000, v67
	v_and_b32_e32 v71, 0xffff0000, v71
	v_and_b32_e32 v68, 0xffff0000, v68
	v_and_b32_e32 v72, 0xffff0000, v72
	v_and_b32_e32 v69, 0xffff0000, v69
	v_and_b32_e32 v73, 0xffff0000, v73
	v_mul_f32_e32 v10, v2, v2
	v_mul_f32_e32 v11, v6, v6
	v_fmac_f32_e32 v10, v66, v66
	v_fmac_f32_e32 v11, v70, v70
	v_fmac_f32_e32 v10, v3, v3
	v_fmac_f32_e32 v11, v7, v7
	v_fmac_f32_e32 v10, v67, v67
	v_fmac_f32_e32 v11, v71, v71
	v_fmac_f32_e32 v10, v4, v4
	v_fmac_f32_e32 v11, v8, v8
	v_fmac_f32_e32 v10, v68, v68
	v_fmac_f32_e32 v11, v72, v72
	v_fmac_f32_e32 v10, v5, v5
	v_fmac_f32_e32 v11, v9, v9
	v_fmac_f32_e32 v10, v69, v69
	v_fmac_f32_e32 v11, v73, v73
	s_nop 1
	v_add_f32_dpp v10, v10, v10 quad_perm:[1,0,3,2] row_mask:0xf bank_mask:0xf
	v_add_f32_dpp v11, v11, v11 quad_perm:[1,0,3,2] row_mask:0xf bank_mask:0xf
	s_nop 0
	v_add_f32_dpp v10, v10, v10 quad_perm:[2,3,0,1] row_mask:0xf bank_mask:0xf
	v_add_f32_dpp v11, v11, v11 quad_perm:[2,3,0,1] row_mask:0xf bank_mask:0xf
	s_nop 0
	v_add_f32_dpp v10, v10, v10 row_half_mirror row_mask:0xf bank_mask:0xf
	v_add_f32_dpp v11, v11, v11 row_half_mirror row_mask:0xf bank_mask:0xf
	s_nop 0
	v_max3_f32 v14, v14, v10, v11
	s_waitcnt vmcnt(8)
	v_lshlrev_b32_e32 v2, 16, v74
	v_lshlrev_b32_e32 v6, 16, v78
	v_lshlrev_b32_e32 v3, 16, v75
	v_lshlrev_b32_e32 v7, 16, v79
	v_lshlrev_b32_e32 v4, 16, v76
	v_lshlrev_b32_e32 v8, 16, v80
	v_lshlrev_b32_e32 v5, 16, v77
	v_lshlrev_b32_e32 v9, 16, v81
	v_and_b32_e32 v74, 0xffff0000, v74
	v_and_b32_e32 v78, 0xffff0000, v78
	v_and_b32_e32 v75, 0xffff0000, v75
	v_and_b32_e32 v79, 0xffff0000, v79
	v_and_b32_e32 v76, 0xffff0000, v76
	v_and_b32_e32 v80, 0xffff0000, v80
	v_and_b32_e32 v77, 0xffff0000, v77
	v_and_b32_e32 v81, 0xffff0000, v81
	v_mul_f32_e32 v10, v2, v2
	v_mul_f32_e32 v11, v6, v6
	v_fmac_f32_e32 v10, v74, v74
	v_fmac_f32_e32 v11, v78, v78
	v_fmac_f32_e32 v10, v3, v3
	v_fmac_f32_e32 v11, v7, v7
	v_fmac_f32_e32 v10, v75, v75
	v_fmac_f32_e32 v11, v79, v79
	v_fmac_f32_e32 v10, v4, v4
	v_fmac_f32_e32 v11, v8, v8
	v_fmac_f32_e32 v10, v76, v76
	v_fmac_f32_e32 v11, v80, v80
	v_fmac_f32_e32 v10, v5, v5
	v_fmac_f32_e32 v11, v9, v9
	v_fmac_f32_e32 v10, v77, v77
	v_fmac_f32_e32 v11, v81, v81
	s_nop 1
	v_add_f32_dpp v10, v10, v10 quad_perm:[1,0,3,2] row_mask:0xf bank_mask:0xf
	v_add_f32_dpp v11, v11, v11 quad_perm:[1,0,3,2] row_mask:0xf bank_mask:0xf
	s_nop 0
	v_add_f32_dpp v10, v10, v10 quad_perm:[2,3,0,1] row_mask:0xf bank_mask:0xf
	v_add_f32_dpp v11, v11, v11 quad_perm:[2,3,0,1] row_mask:0xf bank_mask:0xf
	s_nop 0
	v_add_f32_dpp v10, v10, v10 row_half_mirror row_mask:0xf bank_mask:0xf
	v_add_f32_dpp v11, v11, v11 row_half_mirror row_mask:0xf bank_mask:0xf
	s_nop 0
	v_max3_f32 v14, v14, v10, v11
	s_waitcnt vmcnt(6)
; DI void unpack8(uint4 v, float* f) { f[0] = bflo(v.x); f[1] = bfhi(v.x); f[2] = bflo(v.y); f[3] = bfhi(v.y); f[4] = bflo(v.z); f[5] = bfhi(v.z); f[6] = bflo(v.w); f[7] = bfhi(v.w); }
; DI float shx(float v, int m, int lane) { return __int_as_float(__builtin_amdgcn_ds_bpermute((lane ^ m) << 2, __float_as_int(v))); }
; DI void fox_cumsum_unit(const Params& p, int hf, int bl, int fh, unsigned char* shm, int tid) {
;     ...
;   float kmx = 0.f;
; #pragma unroll 4
;   for (int e = 0; e < 16; ++e) {
;     float ssum = 0.f;
; #pragma unroll
;     for (int q = 0; q < 8; ++q) { float f[8]; unpack8(*(const uint4*)(kb + (size_t)e * NP + q * 8), f);
; #pragma unroll
;       for (int z = 0; z < 8; ++z) ssum += f[z] * f[z]; }
;     kmx = fmaxf(kmx, ssum);
;   }
; #pragma unroll
;   for (int o = 32; o >= 1; o >>= 1) kmx = fmaxf(kmx, shx(kmx, o, lane));
;   __syncthreads();
;   if (lane == 0) sWv[16 + wid] = kmx;
	v_lshlrev_b32_e32 v2, 16, v82
	v_lshlrev_b32_e32 v6, 16, v86
	v_lshlrev_b32_e32 v3, 16, v83
	v_lshlrev_b32_e32 v7, 16, v87
	v_lshlrev_b32_e32 v4, 16, v84
	v_lshlrev_b32_e32 v8, 16, v88
	v_lshlrev_b32_e32 v5, 16, v85
	v_lshlrev_b32_e32 v9, 16, v89
	v_and_b32_e32 v82, 0xffff0000, v82
	v_and_b32_e32 v86, 0xffff0000, v86
	v_and_b32_e32 v83, 0xffff0000, v83
	v_and_b32_e32 v87, 0xffff0000, v87
	v_and_b32_e32 v84, 0xffff0000, v84
	v_and_b32_e32 v88, 0xffff0000, v88
	v_and_b32_e32 v85, 0xffff0000, v85
	v_and_b32_e32 v89, 0xffff0000, v89
	v_mul_f32_e32 v10, v2, v2
	v_mul_f32_e32 v11, v6, v6
	v_fmac_f32_e32 v10, v82, v82
	v_fmac_f32_e32 v11, v86, v86
	v_fmac_f32_e32 v10, v3, v3
	v_fmac_f32_e32 v11, v7, v7
	v_fmac_f32_e32 v10, v83, v83
	v_fmac_f32_e32 v11, v87, v87
	v_fmac_f32_e32 v10, v4, v4
	v_fmac_f32_e32 v11, v8, v8
	v_fmac_f32_e32 v10, v84, v84
	v_fmac_f32_e32 v11, v88, v88
	v_fmac_f32_e32 v10, v5, v5
	v_fmac_f32_e32 v11, v9, v9
	v_fmac_f32_e32 v10, v85, v85
	v_fmac_f32_e32 v11, v89, v89
	s_nop 1
	v_add_f32_dpp v10, v10, v10 quad_perm:[1,0,3,2] row_mask:0xf bank_mask:0xf
	v_add_f32_dpp v11, v11, v11 quad_perm:[1,0,3,2] row_mask:0xf bank_mask:0xf
	s_nop 0
	v_add_f32_dpp v10, v10, v10 quad_perm:[2,3,0,1] row_mask:0xf bank_mask:0xf
	v_add_f32_dpp v11, v11, v11 quad_perm:[2,3,0,1] row_mask:0xf bank_mask:0xf
	s_nop 0
	v_add_f32_dpp v10, v10, v10 row_half_mirror row_mask:0xf bank_mask:0xf
	v_add_f32_dpp v11, v11, v11 row_half_mirror row_mask:0xf bank_mask:0xf
	s_nop 0
	v_max3_f32 v14, v14, v10, v11
	s_waitcnt vmcnt(4)
	v_lshlrev_b32_e32 v2, 16, v90
	v_lshlrev_b32_e32 v6, 16, v94
	v_lshlrev_b32_e32 v3, 16, v91
	v_lshlrev_b32_e32 v7, 16, v95
	v_lshlrev_b32_e32 v4, 16, v92
	v_lshlrev_b32_e32 v8, 16, v96
	v_lshlrev_b32_e32 v5, 16, v93
	v_lshlrev_b32_e32 v9, 16, v97
	v_and_b32_e32 v90, 0xffff0000, v90
	v_and_b32_e32 v94, 0xffff0000, v94
	v_and_b32_e32 v91, 0xffff0000, v91
	v_and_b32_e32 v95, 0xffff0000, v95
	v_and_b32_e32 v92, 0xffff0000, v92
	v_and_b32_e32 v96, 0xffff0000, v96
	v_and_b32_e32 v93, 0xffff0000, v93
	v_and_b32_e32 v97, 0xffff0000, v97
	v_mul_f32_e32 v10, v2, v2
	v_mul_f32_e32 v11, v6, v6
	v_fmac_f32_e32 v10, v90, v90
	v_fmac_f32_e32 v11, v94, v94
	v_fmac_f32_e32 v10, v3, v3
	v_fmac_f32_e32 v11, v7, v7
	v_fmac_f32_e32 v10, v91, v91
	v_fmac_f32_e32 v11, v95, v95
	v_fmac_f32_e32 v10, v4, v4
	v_fmac_f32_e32 v11, v8, v8
	v_fmac_f32_e32 v10, v92, v92
	v_fmac_f32_e32 v11, v96, v96
	v_fmac_f32_e32 v10, v5, v5
	v_fmac_f32_e32 v11, v9, v9
	v_fmac_f32_e32 v10, v93, v93
	v_fmac_f32_e32 v11, v97, v97
	s_nop 1
	v_add_f32_dpp v10, v10, v10 quad_perm:[1,0,3,2] row_mask:0xf bank_mask:0xf
	v_add_f32_dpp v11, v11, v11 quad_perm:[1,0,3,2] row_mask:0xf bank_mask:0xf
	s_nop 0
	v_add_f32_dpp v10, v10, v10 quad_perm:[2,3,0,1] row_mask:0xf bank_mask:0xf
	v_add_f32_dpp v11, v11, v11 quad_perm:[2,3,0,1] row_mask:0xf bank_mask:0xf
	s_nop 0
	v_add_f32_dpp v10, v10, v10 row_half_mirror row_mask:0xf bank_mask:0xf
	v_add_f32_dpp v11, v11, v11 row_half_mirror row_mask:0xf bank_mask:0xf
	s_nop 0
	v_max3_f32 v14, v14, v10, v11
	s_waitcnt vmcnt(2)
	v_lshlrev_b32_e32 v2, 16, v98
	v_lshlrev_b32_e32 v6, 16, v102
	v_lshlrev_b32_e32 v3, 16, v99
	v_lshlrev_b32_e32 v7, 16, v103
	v_lshlrev_b32_e32 v4, 16, v100
	v_lshlrev_b32_e32 v8, 16, v104
	v_lshlrev_b32_e32 v5, 16, v101
	v_lshlrev_b32_e32 v9, 16, v105
	v_and_b32_e32 v98, 0xffff0000, v98
	v_and_b32_e32 v102, 0xffff0000, v102
	v_and_b32_e32 v99, 0xffff0000, v99
	v_and_b32_e32 v103, 0xffff0000, v103
	v_and_b32_e32 v100, 0xffff0000, v100
	v_and_b32_e32 v104, 0xffff0000, v104
	v_and_b32_e32 v101, 0xffff0000, v101
	v_and_b32_e32 v105, 0xffff0000, v105
	v_mul_f32_e32 v10, v2, v2
	v_mul_f32_e32 v11, v6, v6
	v_fmac_f32_e32 v10, v98, v98
	v_fmac_f32_e32 v11, v102, v102
	v_fmac_f32_e32 v10, v3, v3
	v_fmac_f32_e32 v11, v7, v7
	v_fmac_f32_e32 v10, v99, v99
	v_fmac_f32_e32 v11, v103, v103
	v_fmac_f32_e32 v10, v4, v4
	v_fmac_f32_e32 v11, v8, v8
	v_fmac_f32_e32 v10, v100, v100
	v_fmac_f32_e32 v11, v104, v104
	v_fmac_f32_e32 v10, v5, v5
	v_fmac_f32_e32 v11, v9, v9
	v_fmac_f32_e32 v10, v101, v101
	v_fmac_f32_e32 v11, v105, v105
	s_nop 1
	v_add_f32_dpp v10, v10, v10 quad_perm:[1,0,3,2] row_mask:0xf bank_mask:0xf
	v_add_f32_dpp v11, v11, v11 quad_perm:[1,0,3,2] row_mask:0xf bank_mask:0xf
	s_nop 0
	v_add_f32_dpp v10, v10, v10 quad_perm:[2,3,0,1] row_mask:0xf bank_mask:0xf
	v_add_f32_dpp v11, v11, v11 quad_perm:[2,3,0,1] row_mask:0xf bank_mask:0xf
	s_nop 0
	v_add_f32_dpp v10, v10, v10 row_half_mirror row_mask:0xf bank_mask:0xf
	v_add_f32_dpp v11, v11, v11 row_half_mirror row_mask:0xf bank_mask:0xf
	s_nop 0
	v_max3_f32 v14, v14, v10, v11
	s_waitcnt vmcnt(0)
	v_lshlrev_b32_e32 v2, 16, v106
	v_lshlrev_b32_e32 v6, 16, v110
	v_lshlrev_b32_e32 v3, 16, v107
	v_lshlrev_b32_e32 v7, 16, v111
	v_lshlrev_b32_e32 v4, 16, v108
	v_lshlrev_b32_e32 v8, 16, v112
	v_lshlrev_b32_e32 v5, 16, v109
	v_lshlrev_b32_e32 v9, 16, v113
	v_and_b32_e32 v106, 0xffff0000, v106
	v_and_b32_e32 v110, 0xffff0000, v110
	v_and_b32_e32 v107, 0xffff0000, v107
	v_and_b32_e32 v111, 0xffff0000, v111
	v_and_b32_e32 v108, 0xffff0000, v108
	v_and_b32_e32 v112, 0xffff0000, v112
	v_and_b32_e32 v109, 0xffff0000, v109
	v_and_b32_e32 v113, 0xffff0000, v113
	v_mul_f32_e32 v10, v2, v2
	v_mul_f32_e32 v11, v6, v6
	v_fmac_f32_e32 v10, v106, v106
	v_fmac_f32_e32 v11, v110, v110
	v_fmac_f32_e32 v10, v3, v3
	v_fmac_f32_e32 v11, v7, v7
	v_fmac_f32_e32 v10, v107, v107
	v_fmac_f32_e32 v11, v111, v111
	v_fmac_f32_e32 v10, v4, v4
	v_fmac_f32_e32 v11, v8, v8
	v_fmac_f32_e32 v10, v108, v108
	v_fmac_f32_e32 v11, v112, v112
	v_fmac_f32_e32 v10, v5, v5
	v_fmac_f32_e32 v11, v9, v9
	v_fmac_f32_e32 v10, v109, v109
	v_fmac_f32_e32 v11, v113, v113
	s_nop 1
	v_add_f32_dpp v10, v10, v10 quad_perm:[1,0,3,2] row_mask:0xf bank_mask:0xf
	v_add_f32_dpp v11, v11, v11 quad_perm:[1,0,3,2] row_mask:0xf bank_mask:0xf
	s_nop 0
	v_add_f32_dpp v10, v10, v10 quad_perm:[2,3,0,1] row_mask:0xf bank_mask:0xf
	v_add_f32_dpp v11, v11, v11 quad_perm:[2,3,0,1] row_mask:0xf bank_mask:0xf
	s_nop 0
	v_add_f32_dpp v10, v10, v10 row_half_mirror row_mask:0xf bank_mask:0xf
	v_add_f32_dpp v11, v11, v11 row_half_mirror row_mask:0xf bank_mask:0xf
	s_nop 0
	v_max3_f32 v14, v14, v10, v11
	v_and_b32_e32 v0, 63, v46
	v_cmp_eq_u32_e32 vcc, 0, v0
	v_xor_b32_e32 v0, 0x80, v47
	ds_bpermute_b32 v0, v0, v14
	v_max_f32_e32 v1, v14, v14
	s_waitcnt lgkmcnt(0)
	s_barrier
; DI float shx(float v, int m, int lane) { return __int_as_float(__builtin_amdgcn_ds_bpermute((lane ^ m) << 2, __float_as_int(v))); }
; DI void fox_cumsum_unit(const Params& p, int hf, int bl, int fh, unsigned char* shm, int tid) {
;     ...
;   for (int o = 32; o >= 1; o >>= 1) kmx = fmaxf(kmx, shx(kmx, o, lane));
;   __syncthreads();
;   if (lane == 0) sWv[16 + wid] = kmx;
	v_max_f32_e32 v0, v0, v0
	v_max_f32_e32 v0, v1, v0
	v_xor_b32_e32 v1, 64, v47
	ds_bpermute_b32 v1, v1, v0
	s_waitcnt lgkmcnt(0)
	v_max_f32_e32 v1, v1, v1
	v_max_f32_e32 v0, v0, v1
	v_xor_b32_e32 v1, 32, v47
	ds_bpermute_b32 v1, v1, v0
	s_waitcnt lgkmcnt(0)
	v_max_f32_e32 v1, v1, v1
	v_max_f32_e32 v0, v0, v1
	v_xor_b32_e32 v1, 16, v47
	ds_bpermute_b32 v1, v1, v0
	s_waitcnt lgkmcnt(0)
	v_max_f32_e32 v1, v1, v1
	v_max_f32_e32 v0, v0, v1
	v_xor_b32_e32 v1, 8, v47
	ds_bpermute_b32 v1, v1, v0
	s_waitcnt lgkmcnt(0)
	v_max_f32_e32 v1, v1, v1
	v_max_f32_e32 v0, v0, v1
	v_xor_b32_e32 v1, 4, v47
	ds_bpermute_b32 v1, v1, v0
	s_and_saveexec_b64 s[0:1], vcc
	s_cbranch_execz .LBB0_349
	s_waitcnt lgkmcnt(0)
	v_max_f32_e32 v1, v1, v1
	v_max_f32_e32 v0, v0, v0
	v_max_f32_e32 v0, v0, v1
	ds_write_b32 v48, v0 offset:64
